# v85 (static prio waves 0-3) + P8 K-loop load segments balanced 12/12 ds_reads (bj=1 B half read one segment early into spare quads)
# baseline (speedup 1.0000x reference)
.LBB0_998:
	s_mul_i32 s47, s85, 0x2c0000
	s_and_b64 s[4:5], s[6:7], exec
	s_mul_i32 s86, s84, 0x2c0000
	s_cselect_b32 s87, s47, s61
	s_cselect_b32 s88, s86, s63
	s_cmp_gt_i32 s85, 0
	s_cselect_b64 s[4:5], -1, 0
	s_lshl_b32 s89, s85, 2
	v_cndmask_b32_e64 v140, 0, 1.0, s[4:5]
	s_mov_b32 s92, 0
	s_or_b32 s90, s89, 2
	v_mov_b32_e32 v142, v140
	v_mov_b32_e32 v143, v140
	s_lshl_b32 s91, s85, 8
	v_add_u32_e32 v130, 0x14000, v155
	ds_read_b128 v[166:169], v130
	ds_read_b128 v[170:173], v130 offset:1024
	ds_read_b128 v[174:177], v130 offset:2048
	ds_read_b128 v[178:181], v130 offset:3072
	v_readfirstlane_b32 s98, v0
	s_nop 0
	s_bitcmp0_b32 s98, 8
	s_cbranch_scc0 .Lprio_4
	s_setprio 1

.LBB0_1003:
	v_add_u32_e32 v130, 0x10000, v155
	ds_read_b128 v[132:135], v130
	ds_read_b128 v[144:147], v130 offset:1024
	ds_read_b128 v[158:161], v130 offset:2048
	ds_read_b128 v[162:165], v130 offset:3072
	s_lshl_b32 s39, s92, 7
	s_add_i32 s93, s61, s39
	s_addk_i32 s39, 0x100
	s_add_i32 s94, s93, 0x80
	s_add_i32 s95, s39, s61
	s_and_b64 s[50:51], s[48:49], exec
	s_cselect_b32 s50, s87, s95
	s_add_i32 s39, s39, s63
	s_and_b64 s[48:49], s[48:49], exec
	s_cselect_b32 s48, s88, s39
	s_or_b32 s49, s48, 0x80
	s_mov_b32 m0, s77
	ds_read_b128 v[182:185], v156
	ds_read_b128 v[186:189], v156 offset:1024
	buffer_load_dwordx4 v151, s[28:31], s94 offen lds
	s_mov_b32 m0, s78
	ds_read_b128 v[190:193], v156 offset:2048
	ds_read_b128 v[194:197], v156 offset:3072
	buffer_load_dwordx4 v153, s[28:31], s94 offen lds
	s_add_i32 s93, s93, 0x160080
	s_mov_b32 m0, s79
	ds_read_b128 v[198:201], v156 offset:4096
	ds_read_b128 v[202:205], v156 offset:5120
	buffer_load_dwordx4 v151, s[28:31], s93 offen lds
	s_mov_b32 m0, s80
	ds_read_b128 v[206:209], v156 offset:6144
	ds_read_b128 v[210:213], v156 offset:7168
	buffer_load_dwordx4 v153, s[28:31], s93 offen lds
	s_waitcnt vmcnt(6)
	s_waitcnt lgkmcnt(0)
	s_barrier
	s_waitcnt lgkmcnt(0)
	v_mfma_f32_16x16x32_bf16 v[126:129], v[132:135], v[182:185], v[126:129]
	v_mfma_f32_16x16x32_bf16 v[126:129], v[144:147], v[186:189], v[126:129]
	v_mfma_f32_16x16x32_bf16 v[110:113], v[144:147], v[194:197], v[110:113]
	v_mfma_f32_16x16x32_bf16 v[110:113], v[132:135], v[190:193], v[110:113]
	v_mfma_f32_16x16x32_bf16 v[94:97], v[132:135], v[198:201], v[94:97]
	v_mfma_f32_16x16x32_bf16 v[94:97], v[144:147], v[202:205], v[94:97]
	v_mfma_f32_16x16x32_bf16 v[78:81], v[144:147], v[210:213], v[78:81]
	v_mfma_f32_16x16x32_bf16 v[78:81], v[132:135], v[206:209], v[78:81]
	v_mfma_f32_16x16x32_bf16 v[74:77], v[162:165], v[210:213], v[74:77]
	v_mfma_f32_16x16x32_bf16 v[74:77], v[158:161], v[206:209], v[74:77]
	v_mfma_f32_16x16x32_bf16 v[90:93], v[158:161], v[198:201], v[90:93]
	v_mfma_f32_16x16x32_bf16 v[90:93], v[162:165], v[202:205], v[90:93]
	v_mfma_f32_16x16x32_bf16 v[106:109], v[162:165], v[194:197], v[106:109]
	v_mfma_f32_16x16x32_bf16 v[106:109], v[158:161], v[190:193], v[106:109]
	v_mfma_f32_16x16x32_bf16 v[122:125], v[158:161], v[182:185], v[122:125]
	v_mfma_f32_16x16x32_bf16 v[122:125], v[162:165], v[186:189], v[122:125]
	v_mfma_f32_16x16x32_bf16 v[118:121], v[166:169], v[182:185], v[118:121]
	v_mfma_f32_16x16x32_bf16 v[118:121], v[170:173], v[186:189], v[118:121]
	v_mfma_f32_16x16x32_bf16 v[102:105], v[170:173], v[194:197], v[102:105]
	v_mfma_f32_16x16x32_bf16 v[102:105], v[166:169], v[190:193], v[102:105]
	v_mfma_f32_16x16x32_bf16 v[86:89], v[166:169], v[198:201], v[86:89]
	v_mfma_f32_16x16x32_bf16 v[86:89], v[170:173], v[202:205], v[86:89]
	v_mfma_f32_16x16x32_bf16 v[70:73], v[170:173], v[210:213], v[70:73]
	v_mfma_f32_16x16x32_bf16 v[70:73], v[166:169], v[206:209], v[70:73]
	v_mfma_f32_16x16x32_bf16 v[66:69], v[178:181], v[210:213], v[66:69]
	v_mfma_f32_16x16x32_bf16 v[66:69], v[174:177], v[206:209], v[66:69]
	v_mfma_f32_16x16x32_bf16 v[82:85], v[174:177], v[198:201], v[82:85]
	v_mfma_f32_16x16x32_bf16 v[82:85], v[178:181], v[202:205], v[82:85]
	v_mfma_f32_16x16x32_bf16 v[98:101], v[178:181], v[194:197], v[98:101]
	v_mfma_f32_16x16x32_bf16 v[98:101], v[174:177], v[190:193], v[98:101]
	v_mfma_f32_16x16x32_bf16 v[114:117], v[174:177], v[182:185], v[114:117]
	v_mfma_f32_16x16x32_bf16 v[114:117], v[178:181], v[186:189], v[114:117]
	s_barrier
	v_add_u32_e32 v130, 0x1c000, v155
	ds_read_b128 v[236:239], v130
	ds_read_b128 v[240:243], v130 offset:1024
	ds_read_b128 v[244:247], v130 offset:2048
	ds_read_b128 v[248:251], v130 offset:3072
	s_add_i32 s51, s48, 0x160000
	s_mov_b32 m0, s66
	s_mov_b32 s39, s31
	ds_read_b128 v[182:185], v156 offset:16384
	ds_read_b128 v[186:189], v156 offset:17408
	buffer_load_dwordx4 v152, s[36:39], s51 offen lds
	s_mov_b32 m0, s67
	ds_read_b128 v[190:193], v156 offset:18432
	ds_read_b128 v[194:197], v156 offset:19456
	buffer_load_dwordx4 v154, s[36:39], s51 offen lds
	s_mov_b32 m0, s64
	ds_read_b128 v[198:201], v156 offset:20480
	ds_read_b128 v[202:205], v156 offset:21504
	buffer_load_dwordx4 v152, s[36:39], s48 offen lds
	s_mov_b32 m0, s65
	ds_read_b128 v[206:209], v156 offset:22528
	ds_read_b128 v[210:213], v156 offset:23552
	buffer_load_dwordx4 v154, s[36:39], s48 offen lds
	s_waitcnt vmcnt(6)
	s_waitcnt lgkmcnt(0)
	s_barrier
	s_waitcnt lgkmcnt(0)
	v_mfma_f32_16x16x32_bf16 v[62:65], v[132:135], v[182:185], v[62:65]
	v_mfma_f32_16x16x32_bf16 v[62:65], v[144:147], v[186:189], v[62:65]
	v_mfma_f32_16x16x32_bf16 v[46:49], v[144:147], v[194:197], v[46:49]
	v_mfma_f32_16x16x32_bf16 v[46:49], v[132:135], v[190:193], v[46:49]
	v_mfma_f32_16x16x32_bf16 v[30:33], v[132:135], v[198:201], v[30:33]
	v_mfma_f32_16x16x32_bf16 v[30:33], v[144:147], v[202:205], v[30:33]
	v_mfma_f32_16x16x32_bf16 v[14:17], v[144:147], v[210:213], v[14:17]
	v_mfma_f32_16x16x32_bf16 v[14:17], v[132:135], v[206:209], v[14:17]
	v_mfma_f32_16x16x32_bf16 v[10:13], v[162:165], v[210:213], v[10:13]
	v_mfma_f32_16x16x32_bf16 v[10:13], v[158:161], v[206:209], v[10:13]
	v_mfma_f32_16x16x32_bf16 v[26:29], v[158:161], v[198:201], v[26:29]
	v_mfma_f32_16x16x32_bf16 v[26:29], v[162:165], v[202:205], v[26:29]
	v_mfma_f32_16x16x32_bf16 v[42:45], v[162:165], v[194:197], v[42:45]
	v_mfma_f32_16x16x32_bf16 v[42:45], v[158:161], v[190:193], v[42:45]
	v_mfma_f32_16x16x32_bf16 v[58:61], v[158:161], v[182:185], v[58:61]
	v_mfma_f32_16x16x32_bf16 v[58:61], v[162:165], v[186:189], v[58:61]
	v_mfma_f32_16x16x32_bf16 v[54:57], v[166:169], v[182:185], v[54:57]
	v_mfma_f32_16x16x32_bf16 v[54:57], v[170:173], v[186:189], v[54:57]
	v_mfma_f32_16x16x32_bf16 v[38:41], v[170:173], v[194:197], v[38:41]
	v_mfma_f32_16x16x32_bf16 v[38:41], v[166:169], v[190:193], v[38:41]
	v_mfma_f32_16x16x32_bf16 v[22:25], v[166:169], v[198:201], v[22:25]
	v_mfma_f32_16x16x32_bf16 v[22:25], v[170:173], v[202:205], v[22:25]
	v_mfma_f32_16x16x32_bf16 v[6:9], v[170:173], v[210:213], v[6:9]
	v_mfma_f32_16x16x32_bf16 v[6:9], v[166:169], v[206:209], v[6:9]
	v_mfma_f32_16x16x32_bf16 v[2:5], v[178:181], v[210:213], v[2:5]
	v_mfma_f32_16x16x32_bf16 v[2:5], v[174:177], v[206:209], v[2:5]
	v_mfma_f32_16x16x32_bf16 v[18:21], v[174:177], v[198:201], v[18:21]
	v_mfma_f32_16x16x32_bf16 v[18:21], v[178:181], v[202:205], v[18:21]
	v_mfma_f32_16x16x32_bf16 v[34:37], v[178:181], v[194:197], v[34:37]
	v_mfma_f32_16x16x32_bf16 v[34:37], v[174:177], v[190:193], v[34:37]
	v_mfma_f32_16x16x32_bf16 v[50:53], v[174:177], v[182:185], v[50:53]
	v_mfma_f32_16x16x32_bf16 v[50:53], v[178:181], v[186:189], v[50:53]
	s_barrier
	v_add_u32_e32 v130, 0x18000, v155
	ds_read_b128 v[132:135], v130
	ds_read_b128 v[144:147], v130 offset:1024
	ds_read_b128 v[158:161], v130 offset:2048
	ds_read_b128 v[162:165], v130 offset:3072
	s_mov_b32 m0, s62
	ds_read_b128 v[182:185], v156 offset:32768
	ds_read_b128 v[186:189], v156 offset:33792
	buffer_load_dwordx4 v151, s[28:31], s50 offen lds
	s_mov_b32 m0, s68
	ds_read_b128 v[190:193], v156 offset:34816
	ds_read_b128 v[194:197], v156 offset:35840
	buffer_load_dwordx4 v153, s[28:31], s50 offen lds
	s_add_i32 s50, s50, 0x160000
	s_mov_b32 m0, s69
	ds_read_b128 v[198:201], v156 offset:36864
	ds_read_b128 v[202:205], v156 offset:37888
	buffer_load_dwordx4 v151, s[28:31], s50 offen lds
	s_mov_b32 m0, s70
	ds_read_b128 v[206:209], v156 offset:38912
	ds_read_b128 v[210:213], v156 offset:39936
	buffer_load_dwordx4 v153, s[28:31], s50 offen lds
	s_waitcnt vmcnt(6)
	s_waitcnt lgkmcnt(0)
	s_barrier
	s_waitcnt lgkmcnt(0)
	v_mfma_f32_16x16x32_bf16 v[126:129], v[132:135], v[182:185], v[126:129]
	v_mfma_f32_16x16x32_bf16 v[126:129], v[144:147], v[186:189], v[126:129]
	v_mfma_f32_16x16x32_bf16 v[110:113], v[144:147], v[194:197], v[110:113]
	v_mfma_f32_16x16x32_bf16 v[110:113], v[132:135], v[190:193], v[110:113]
	v_mfma_f32_16x16x32_bf16 v[94:97], v[132:135], v[198:201], v[94:97]
	v_mfma_f32_16x16x32_bf16 v[94:97], v[144:147], v[202:205], v[94:97]
	v_mfma_f32_16x16x32_bf16 v[78:81], v[144:147], v[210:213], v[78:81]
	v_mfma_f32_16x16x32_bf16 v[78:81], v[132:135], v[206:209], v[78:81]
	v_mfma_f32_16x16x32_bf16 v[74:77], v[162:165], v[210:213], v[74:77]
	v_mfma_f32_16x16x32_bf16 v[74:77], v[158:161], v[206:209], v[74:77]
	v_mfma_f32_16x16x32_bf16 v[90:93], v[158:161], v[198:201], v[90:93]
	v_mfma_f32_16x16x32_bf16 v[90:93], v[162:165], v[202:205], v[90:93]
	v_mfma_f32_16x16x32_bf16 v[106:109], v[162:165], v[194:197], v[106:109]
	v_mfma_f32_16x16x32_bf16 v[106:109], v[158:161], v[190:193], v[106:109]
	v_mfma_f32_16x16x32_bf16 v[122:125], v[158:161], v[182:185], v[122:125]
	v_mfma_f32_16x16x32_bf16 v[122:125], v[162:165], v[186:189], v[122:125]
	v_mfma_f32_16x16x32_bf16 v[118:121], v[236:239], v[182:185], v[118:121]
	v_mfma_f32_16x16x32_bf16 v[118:121], v[240:243], v[186:189], v[118:121]
	v_mfma_f32_16x16x32_bf16 v[102:105], v[240:243], v[194:197], v[102:105]
	v_mfma_f32_16x16x32_bf16 v[102:105], v[236:239], v[190:193], v[102:105]
	v_mfma_f32_16x16x32_bf16 v[86:89], v[236:239], v[198:201], v[86:89]
	v_mfma_f32_16x16x32_bf16 v[86:89], v[240:243], v[202:205], v[86:89]
	v_mfma_f32_16x16x32_bf16 v[70:73], v[240:243], v[210:213], v[70:73]
	v_mfma_f32_16x16x32_bf16 v[70:73], v[236:239], v[206:209], v[70:73]
	v_mfma_f32_16x16x32_bf16 v[66:69], v[248:251], v[210:213], v[66:69]
	v_mfma_f32_16x16x32_bf16 v[66:69], v[244:247], v[206:209], v[66:69]
	v_mfma_f32_16x16x32_bf16 v[82:85], v[244:247], v[198:201], v[82:85]
	v_mfma_f32_16x16x32_bf16 v[82:85], v[248:251], v[202:205], v[82:85]
	v_mfma_f32_16x16x32_bf16 v[98:101], v[248:251], v[194:197], v[98:101]
	v_mfma_f32_16x16x32_bf16 v[98:101], v[244:247], v[190:193], v[98:101]
	v_mfma_f32_16x16x32_bf16 v[114:117], v[244:247], v[182:185], v[114:117]
	v_mfma_f32_16x16x32_bf16 v[114:117], v[248:251], v[186:189], v[114:117]
	s_barrier
	v_add_u32_e32 v130, 0x14000, v155
	ds_read_b128 v[166:169], v130
	ds_read_b128 v[170:173], v130 offset:1024
	ds_read_b128 v[174:177], v130 offset:2048
	ds_read_b128 v[178:181], v130 offset:3072
	s_add_i32 s48, s48, 0x160080
	s_mov_b32 m0, s74
	ds_read_b128 v[182:185], v156 offset:49152
	ds_read_b128 v[186:189], v156 offset:50176
	buffer_load_dwordx4 v152, s[36:39], s48 offen lds
	s_mov_b32 m0, s75
	ds_read_b128 v[190:193], v156 offset:51200
	ds_read_b128 v[194:197], v156 offset:52224
	buffer_load_dwordx4 v154, s[36:39], s48 offen lds
	s_mov_b32 m0, s72
	ds_read_b128 v[198:201], v156 offset:53248
	ds_read_b128 v[202:205], v156 offset:54272
	buffer_load_dwordx4 v152, s[36:39], s49 offen lds
	s_mov_b32 m0, s73
	ds_read_b128 v[206:209], v156 offset:55296
	ds_read_b128 v[210:213], v156 offset:56320
	buffer_load_dwordx4 v154, s[36:39], s49 offen lds
	s_waitcnt vmcnt(6)
	s_waitcnt lgkmcnt(0)
	s_barrier
	s_waitcnt lgkmcnt(0)
	v_mfma_f32_16x16x32_bf16 v[62:65], v[132:135], v[182:185], v[62:65]
	v_mfma_f32_16x16x32_bf16 v[62:65], v[144:147], v[186:189], v[62:65]
	v_mfma_f32_16x16x32_bf16 v[46:49], v[144:147], v[194:197], v[46:49]
	v_mfma_f32_16x16x32_bf16 v[46:49], v[132:135], v[190:193], v[46:49]
	v_mfma_f32_16x16x32_bf16 v[30:33], v[132:135], v[198:201], v[30:33]
	v_mfma_f32_16x16x32_bf16 v[30:33], v[144:147], v[202:205], v[30:33]
	v_mfma_f32_16x16x32_bf16 v[14:17], v[144:147], v[210:213], v[14:17]
	v_mfma_f32_16x16x32_bf16 v[14:17], v[132:135], v[206:209], v[14:17]
	v_mfma_f32_16x16x32_bf16 v[10:13], v[162:165], v[210:213], v[10:13]
	v_mfma_f32_16x16x32_bf16 v[10:13], v[158:161], v[206:209], v[10:13]
	v_mfma_f32_16x16x32_bf16 v[26:29], v[158:161], v[198:201], v[26:29]
	v_mfma_f32_16x16x32_bf16 v[26:29], v[162:165], v[202:205], v[26:29]
	v_mfma_f32_16x16x32_bf16 v[42:45], v[162:165], v[194:197], v[42:45]
	v_mfma_f32_16x16x32_bf16 v[42:45], v[158:161], v[190:193], v[42:45]
	v_mfma_f32_16x16x32_bf16 v[58:61], v[158:161], v[182:185], v[58:61]
	v_mfma_f32_16x16x32_bf16 v[58:61], v[162:165], v[186:189], v[58:61]
	v_mfma_f32_16x16x32_bf16 v[54:57], v[236:239], v[182:185], v[54:57]
	v_mfma_f32_16x16x32_bf16 v[54:57], v[240:243], v[186:189], v[54:57]
	v_mfma_f32_16x16x32_bf16 v[38:41], v[240:243], v[194:197], v[38:41]
	v_mfma_f32_16x16x32_bf16 v[38:41], v[236:239], v[190:193], v[38:41]
	v_mfma_f32_16x16x32_bf16 v[22:25], v[236:239], v[198:201], v[22:25]
	v_mfma_f32_16x16x32_bf16 v[22:25], v[240:243], v[202:205], v[22:25]
	v_mfma_f32_16x16x32_bf16 v[6:9], v[240:243], v[210:213], v[6:9]
	v_mfma_f32_16x16x32_bf16 v[6:9], v[236:239], v[206:209], v[6:9]
	v_mfma_f32_16x16x32_bf16 v[2:5], v[248:251], v[210:213], v[2:5]
	v_mfma_f32_16x16x32_bf16 v[2:5], v[244:247], v[206:209], v[2:5]
	v_mfma_f32_16x16x32_bf16 v[18:21], v[244:247], v[198:201], v[18:21]
	v_mfma_f32_16x16x32_bf16 v[18:21], v[248:251], v[202:205], v[18:21]
	v_mfma_f32_16x16x32_bf16 v[34:37], v[248:251], v[194:197], v[34:37]
	v_mfma_f32_16x16x32_bf16 v[34:37], v[244:247], v[190:193], v[34:37]
	v_mfma_f32_16x16x32_bf16 v[50:53], v[244:247], v[182:185], v[50:53]
	v_mfma_f32_16x16x32_bf16 v[50:53], v[248:251], v[186:189], v[50:53]
	s_barrier
	s_add_i32 s39, s92, 2
	s_cmpk_gt_u32 s92, 0x55
	s_cbranch_scc1 .LBB0_1005
	s_mov_b32 s92, s39
	s_branch .LBB0_999
